# XCD-aware tile maps for P6 (cn=(blk>>3)&3, rm=8*(blk&7)+(blk>>5)) and P5 (8 row panels per XCD, 4 col panels per round) on top of v051
# baseline (speedup 1.0000x reference)
.LBB0_342:
	s_bfe_u32 s98, s54, 0x50003
	s_lshr_b32 s0, s54, 8
	s_lshl_b32 s0, s0, 5
	s_add_i32 s98, s98, s0
	s_and_b32 s0, s54, 7
	s_lshl_b32 s0, s0, 3
	s_and_b32 s1, s98, 7
	s_or_b32 s34, s0, s1
	s_lshr_b32 s98, s98, 3
	s_cmp_lg_u32 s54, s10
	s_cbranch_scc1 .LBB0_354
	s_and_saveexec_b64 s[36:37], s[2:3]
	s_cbranch_execz .LBB0_353
	s_lshl_b32 s0, s34, 4
	s_ashr_i32 s1, s0, 31
	s_lshl_b64 s[0:1], s[0:1], 2
	s_add_u32 s38, s11, s0
	s_addc_u32 s39, s33, s1
	s_mov_b32 s35, 0x400001
	s_branch .LBB0_346

.LBB0_356:
	s_or_b64 exec, exec, s[36:37]
	v_mov_b32_e32 v2, v0
	v_lshlrev_b32_e32 v3, 4, v2
	v_bfe_i32 v2, v2, 27, 1
	v_lshrrev_b32_e32 v2, 22, v2
	v_add_u32_e32 v2, v3, v2
	v_ashrrev_i32_e32 v10, 10, v2
	v_mul_i32_i24_e32 v2, 0x400, v10
	v_sub_u32_e32 v2, v3, v2
	v_add_u32_e32 v4, 0x2000, v3
	v_lshrrev_b32_e32 v3, 4, v2
	v_bitop3_b32 v2, v3, v2, 32 bitop3:0x6c
	v_ashrrev_i32_e32 v5, 31, v2
	v_lshrrev_b32_e32 v5, 26, v5
	v_add_u32_e32 v5, v2, v5
	v_ashrrev_i32_e32 v12, 6, v5
	v_and_b32_e32 v5, 0xc0, v5
	v_sub_u32_e32 v2, v2, v5
	s_waitcnt vmcnt(0)
	v_ashrrev_i16_sdwa v14, v153, sext(v2) dst_sel:DWORD dst_unused:UNUSED_PAD src0_sel:DWORD src1_sel:BYTE_0
	v_ashrrev_i32_e32 v2, 31, v4
	v_lshrrev_b32_e32 v2, 22, v2
	v_add_u32_e32 v2, v4, v2
	v_ashrrev_i32_e32 v11, 10, v2
	v_mul_i32_i24_e32 v2, 0x400, v11
	v_sub_u32_e32 v2, v4, v2
	s_mov_b32 s36, s98
	v_lshrrev_b32_e32 v4, 4, v2
	s_ashr_i32 s37, s36, 31
	v_bitop3_b32 v2, v4, v2, 32 bitop3:0x6c
	s_lshl_b64 s[40:41], s[36:37], 19
	v_ashrrev_i32_e32 v5, 31, v2
	s_add_u32 s38, s42, s40
	v_lshrrev_b32_e32 v5, 26, v5
	s_addc_u32 s39, s43, s41
	s_ashr_i32 s35, s34, 31
	v_lshlrev_b32_e32 v3, 3, v10
	v_add_u32_e32 v5, v2, v5
	s_lshl_b64 s[46:47], s[34:35], 19
	v_and_b32_e32 v3, 0x3ffff0, v3
	v_lshlrev_b32_e32 v6, 5, v10
	v_lshlrev_b32_e32 v4, 3, v11
	v_ashrrev_i32_e32 v15, 6, v5
	v_and_b32_e32 v5, 0xc0, v5
	s_waitcnt lgkmcnt(0)
	s_add_u32 s48, s12, s46
	v_readfirstlane_b32 s0, v0
	v_add_u32_e32 v3, v12, v3
	v_and_b32_e32 v13, 32, v6
	v_and_b32_e32 v4, 0x3ffff0, v4
	v_lshlrev_b32_e32 v6, 5, v11
	v_sub_u32_e32 v2, v2, v5
	s_addc_u32 s49, s13, s47
	s_lshl_b32 s0, s0, 4
	v_add_u32_e32 v4, v15, v4
	v_and_b32_e32 v16, 32, v6
	v_ashrrev_i16_sdwa v17, v153, sext(v2) dst_sel:DWORD dst_unused:UNUSED_PAD src0_sel:DWORD src1_sel:BYTE_0
	v_lshl_or_b32 v2, v3, 10, v13
	v_lshl_or_b32 v3, v4, 10, v16
	s_and_b32 s35, s0, 0xfffffc00
	v_add_u32_sdwa v130, v2, sext(v14) dst_sel:DWORD dst_unused:UNUSED_PAD src0_sel:DWORD src1_sel:WORD_0
	v_add_u32_sdwa v132, v3, sext(v17) dst_sel:DWORD dst_unused:UNUSED_PAD src0_sel:DWORD src1_sel:WORD_0
	v_lshlrev_b64 v[18:19], 1, v[130:131]
	s_add_i32 s37, s35, 0x10000
	v_mov_b32_e32 v133, v131
	v_lshl_add_u64 v[2:3], s[48:49], 0, v[18:19]
	s_mov_b32 m0, s37
	v_lshlrev_b64 v[20:21], 1, v[132:133]
	s_add_i32 s55, s35, 0x12000
	global_load_lds_dwordx4 v[2:3], off
	v_lshl_add_u64 v[6:7], s[48:49], 0, v[20:21]
	s_mov_b32 m0, s55
	s_add_i32 s56, s35, 0x2000
	global_load_lds_dwordx4 v[6:7], off
	v_lshl_add_u64 v[8:9], s[38:39], 0, v[18:19]
	s_mov_b32 m0, s35
	s_add_u32 s0, s48, 0x40000
	global_load_lds_dwordx4 v[8:9], off
	v_lshl_add_u64 v[4:5], s[38:39], 0, v[20:21]
	s_mov_b32 m0, s56
	s_addc_u32 s1, s49, 0
	s_add_i32 s57, s35, 0x14000
	global_load_lds_dwordx4 v[4:5], off
	v_lshl_add_u64 v[22:23], s[0:1], 0, v[18:19]
	s_mov_b32 m0, s57
	s_add_i32 s58, s35, 0x16000
	global_load_lds_dwordx4 v[22:23], off
	v_lshl_add_u64 v[22:23], s[0:1], 0, v[20:21]
	s_add_u32 s0, s38, 0x40000
	s_mov_b32 m0, s58
	s_addc_u32 s1, s39, 0
	s_add_i32 s59, s35, 0x4000
	global_load_lds_dwordx4 v[22:23], off
	v_lshl_add_u64 v[18:19], s[0:1], 0, v[18:19]
	s_mov_b32 m0, s59
	s_add_i32 s60, s35, 0x6000
	global_load_lds_dwordx4 v[18:19], off
	v_lshl_add_u64 v[18:19], s[0:1], 0, v[20:21]
	s_mov_b32 m0, s60
	s_nop 0
	global_load_lds_dwordx4 v[18:19], off
	s_and_saveexec_b64 s[50:51], s[6:7]
	s_cbranch_execz .LBB0_358
	s_barrier

.LBB0_362:
	s_or_b64 exec, exec, s[38:39]
	s_waitcnt vmcnt(0)
	s_barrier
	s_load_dword s0, s[16:17], 0x0
	s_waitcnt lgkmcnt(0)
	s_add_i32 s54, s0, s54
	s_cmpk_gt_i32 s54, 0x57f
	s_cselect_b64 s[38:39], -1, 0
	s_cmpk_lt_i32 s54, 0x580
	s_cselect_b64 s[0:1], -1, 0
	s_and_b64 s[0:1], s[2:3], s[0:1]
	s_and_saveexec_b64 s[40:41], s[0:1]
	s_cbranch_execz .LBB0_341
	s_bfe_u32 s99, s54, 0x50003
	s_lshr_b32 s0, s54, 8
	s_lshl_b32 s0, s0, 5
	s_add_i32 s99, s99, s0
	s_and_b32 s0, s54, 7
	s_lshl_b32 s0, s0, 3
	s_and_b32 s1, s99, 7
	s_or_b32 s0, s0, s1
	s_lshl_b32 s0, s0, 4
	s_ashr_i32 s1, s0, 31
	s_lshl_b64 s[0:1], s[0:1], 2
	s_add_u32 s46, s11, s0
	s_addc_u32 s47, s33, s1
	s_mov_b32 s35, 0x400001
	s_branch .LBB0_365
